# adds: final RMSNorm loop no longer waits for its previous stores before issuing the next rows' loads
# speedup vs baseline: 1.0059x; 1.0004x over previous
; __global__ void __launch_bounds__(512, 2) fwd_megakernel(Params P) {
;     ...
;         for (int r0 = gw; r0 < MT; r0 += 4 * NGW) {
;             float sv[4]; u32x4 v[4][2];
; #pragma unroll
;             for (int q = 0; q < 4; ++q) { const int r = min(r0 + q * NGW, MT - 1); sv[q] = (lane < 16) ? SS[(size_t)r * 16 + lane] : 0.f;
;                 v[q][0] = ((const u32x4*)(XB + (size_t)r * 1024))[2 * lane]; v[q][1] = ((const u32x4*)(XB + (size_t)r * 1024))[2 * lane + 1]; }
.LBB0_1062:
	s_ashr_i32 s3, s2, 31
	v_mov_b32_e32 v16, 0
	s_and_saveexec_b64 s[0:1], vcc
	s_cbranch_execz .LBB0_1064
	s_lshl_b64 s[4:5], s[2:3], 6
	v_lshl_add_u64 v[16:17], v[50:51], 0, s[4:5]
	global_load_dword v16, v[16:17], off
